# V3 = V2 + FoX steady-loop forget-bias LDS reads batched with grouped waits and no-op counted waits removed + NSA QK K-fragment reads batched into spare VGPRs
# speedup vs baseline: 1.0075x; 1.0036x over previous
.LBB0_787:
	v_add_u32_e32 v180, s10, v229
	ds_read_b64_tr_b16 v[176:177], v180 offset:24576
	ds_read_b64_tr_b16 v[178:179], v180 offset:25088
	v_add_f32_e32 v80, v64, v65
	v_add_f32_e32 v80, v66, v80
	v_add_f32_e32 v80, v67, v80
	v_add_f32_e32 v80, v68, v80
	v_add_f32_e32 v96, v69, v80
	v_mfma_f32_32x32x16_bf16 v[80:95], v[172:175], v[128:131], v[32:47]
	v_cvt_pk_bf16_f32 v140, v64, v65
	v_cvt_pk_bf16_f32 v141, v66, v67
	ds_read_b64_tr_b16 v[172:173], v180 offset:28672
	ds_read_b64_tr_b16 v[174:175], v180 offset:29184
	v_add_f32_e32 v64, v70, v96
	v_add_f32_e32 v64, v71, v64
	v_add_f32_e32 v64, v72, v64
	v_add_f32_e32 v64, v73, v64
	v_cvt_pk_bf16_f32 v142, v68, v69
	v_cvt_pk_bf16_f32 v143, v70, v71
	v_mfma_f32_32x32x16_bf16 v[96:111], v[168:171], v[128:131], v[32:47]
	ds_read_b64_tr_b16 v[168:169], v180 offset:25600
	ds_read_b64_tr_b16 v[170:171], v180 offset:26112
	v_mfma_f32_32x32x16_bf16 v[80:95], v[164:167], v[120:123], v[80:95]
	v_add_f32_e32 v64, v74, v64
	v_add_f32_e32 v64, v75, v64
	v_add_f32_e32 v64, v76, v64
	v_add_f32_e32 v64, v77, v64
	v_cvt_pk_bf16_f32 v136, v72, v73
	v_cvt_pk_bf16_f32 v137, v74, v75
	ds_read_b64_tr_b16 v[164:165], v180 offset:29696
	ds_read_b64_tr_b16 v[166:167], v180 offset:30208
	v_add_f32_e32 v64, v78, v64
	v_add_f32_e32 v64, v79, v64
	v_add_f32_e32 v64, v48, v64
	v_add_f32_e32 v64, v49, v64
	v_cvt_pk_bf16_f32 v138, v76, v77
	v_cvt_pk_bf16_f32 v139, v78, v79
	v_mfma_f32_32x32x16_bf16 v[96:111], v[160:163], v[120:123], v[96:111]
	ds_read_b64_tr_b16 v[160:161], v180 offset:26624
	ds_read_b64_tr_b16 v[162:163], v180 offset:27136
	v_mfma_f32_32x32x16_bf16 v[80:95], v[156:159], v[116:119], v[80:95]
	v_add_f32_e32 v64, v50, v64
	v_add_f32_e32 v64, v51, v64
	v_add_f32_e32 v64, v52, v64
	v_add_f32_e32 v64, v53, v64
	v_cvt_pk_bf16_f32 v132, v48, v49
	v_cvt_pk_bf16_f32 v133, v50, v51
	ds_read_b64_tr_b16 v[156:157], v180 offset:30720
	ds_read_b64_tr_b16 v[158:159], v180 offset:31232
	v_add_f32_e32 v48, v54, v64
	v_add_f32_e32 v48, v55, v48
	v_add_f32_e32 v48, v56, v48
	v_add_f32_e32 v48, v57, v48
	v_cvt_pk_bf16_f32 v134, v52, v53
	v_cvt_pk_bf16_f32 v135, v54, v55
	v_mfma_f32_32x32x16_bf16 v[96:111], v[152:155], v[116:119], v[96:111]
	ds_read_b64_tr_b16 v[152:153], v180 offset:27648
	ds_read_b64_tr_b16 v[154:155], v180 offset:28160
	v_mfma_f32_32x32x16_bf16 v[80:95], v[148:151], v[112:115], v[80:95]
	v_add_f32_e32 v48, v58, v48
	v_add_f32_e32 v48, v59, v48
	v_add_f32_e32 v48, v60, v48
	v_add_f32_e32 v48, v61, v48
	v_cvt_pk_bf16_f32 v124, v56, v57
	v_cvt_pk_bf16_f32 v125, v58, v59
	ds_read_b64_tr_b16 v[148:149], v180 offset:31744
	ds_read_b64_tr_b16 v[150:151], v180 offset:32256
	v_add_f32_e32 v48, v62, v48
	v_add_f32_e32 v48, v63, v48
	v_add_f32_e32 v180, 0, v48
	v_cvt_pk_bf16_f32 v126, v60, v61
	v_cvt_pk_bf16_f32 v127, v62, v63
	v_mfma_f32_32x32x16_bf16 v[96:111], v[144:147], v[112:115], v[96:111]
	s_waitcnt lgkmcnt(8)
	ds_read_b128 v[64:67], v196
	ds_read_b128 v[68:71], v196 offset:32
	ds_read_b128 v[72:75], v196 offset:64
	ds_read_b128 v[76:79], v196 offset:96
	ds_read_b128 v[52:55], v196 offset:160
	ds_read_b128 v[56:59], v196 offset:192
	ds_read_b128 v[60:63], v196 offset:224
	v_lshl_add_u64 v[48:49], v[194:195], 0, s[24:25]
	s_add_i32 s0, s36, s65
	s_mov_b32 m0, s0
	s_nop 0
	global_load_lds_dwordx4 v[48:49], off
	v_lshl_add_u64 v[48:49], v[192:193], 0, s[24:25]
	s_add_i32 s0, s1, s68
	s_mov_b32 m0, s0
	s_nop 0
	global_load_lds_dwordx4 v[48:49], off
	ds_read_b128 v[48:51], v196 offset:128
	s_waitcnt lgkmcnt(4)
	v_pk_add_f32 v[64:65], v[80:81], v[64:65]
	v_pk_add_f32 v[66:67], v[82:83], v[66:67]
	v_pk_add_f32 v[68:69], v[84:85], v[68:69]
	v_pk_add_f32 v[70:71], v[86:87], v[70:71]
	v_pk_add_f32 v[72:73], v[88:89], v[72:73]
	v_pk_add_f32 v[74:75], v[90:91], v[74:75]
	v_pk_add_f32 v[76:77], v[92:93], v[76:77]
	v_pk_add_f32 v[78:79], v[94:95], v[78:79]
	s_waitcnt lgkmcnt(1)
	v_pk_add_f32 v[52:53], v[100:101], v[52:53]
	v_pk_add_f32 v[54:55], v[102:103], v[54:55]
	v_pk_add_f32 v[56:57], v[104:105], v[56:57]
	v_pk_add_f32 v[58:59], v[106:107], v[58:59]
	v_pk_add_f32 v[60:61], v[108:109], v[60:61]
	v_pk_add_f32 v[62:63], v[110:111], v[62:63]
	s_waitcnt lgkmcnt(0)
	v_pk_add_f32 v[48:49], v[96:97], v[48:49]
	v_pk_add_f32 v[50:51], v[98:99], v[50:51]
	v_max_f32_e32 v80, v64, v65
	v_max3_f32 v81, v66, v67, v49
	v_max3_f32 v80, v80, v48, v50
	v_max3_f32 v80, v80, v51, v68
	v_max3_f32 v81, v81, v70, v71
	v_max3_f32 v80, v80, v69, v52
	v_max3_f32 v81, v81, v54, v55
	v_max3_f32 v80, v80, v53, v72
	v_max3_f32 v81, v81, v74, v75
	v_max3_f32 v80, v80, v73, v56
	v_max3_f32 v81, v81, v58, v59
	v_max3_f32 v80, v80, v57, v76
	v_max3_f32 v81, v81, v78, v79
	v_max3_f32 v80, v80, v77, v60
	v_max3_f32 v81, v81, v62, v63
	v_max3_f32 v80, v80, v61, v81
	v_mov_b32_e32 v81, v80
	s_nop 1
	v_permlane32_swap_b32_e32 v80, v81
	v_max_f32_e32 v81, v81, v81
	v_max_f32_e32 v80, v80, v80
	v_max_f32_e32 v80, v80, v81
	v_cmp_lt_f32_e32 vcc, s61, v80
	s_cmp_lg_u64 vcc, 0
	v_add_f32_e32 v197, v231, v180
	s_cselect_b64 s[10:11], -1, 0
	s_cbranch_vccnz .LBB0_795

.LBB0_790:
	s_add_i32 s0, s1, 0x2000
	s_cmpk_lg_i32 s1, 0x4000
	s_cselect_b32 s71, s0, 0
	v_add_u32_e32 v198, s36, v229
	ds_read_b64_tr_b16 v[160:161], v198 offset:24576
	ds_read_b64_tr_b16 v[162:163], v198 offset:25088
	v_add_f32_e32 v80, v64, v65
	v_add_f32_e32 v80, v66, v80
	v_add_f32_e32 v80, v67, v80
	v_add_f32_e32 v80, v68, v80
	v_add_f32_e32 v100, v69, v80
	v_mfma_f32_32x32x16_bf16 v[80:95], v[96:99], v[128:131], v[32:47]
	v_cvt_pk_bf16_f32 v140, v64, v65
	v_cvt_pk_bf16_f32 v141, v66, v67
	ds_read_b64_tr_b16 v[156:157], v198 offset:28672
	ds_read_b64_tr_b16 v[158:159], v198 offset:29184
	v_add_f32_e32 v64, v70, v100
	v_add_f32_e32 v64, v71, v64
	v_add_f32_e32 v64, v72, v64
	v_add_f32_e32 v64, v73, v64
	v_cvt_pk_bf16_f32 v142, v68, v69
	v_cvt_pk_bf16_f32 v143, v70, v71
	v_mfma_f32_32x32x16_bf16 v[96:111], v[180:183], v[128:131], v[32:47]
	ds_read_b64_tr_b16 v[152:153], v198 offset:25600
	ds_read_b64_tr_b16 v[154:155], v198 offset:26112
	v_mfma_f32_32x32x16_bf16 v[80:95], v[184:187], v[120:123], v[80:95]
	v_add_f32_e32 v64, v74, v64
	v_add_f32_e32 v64, v75, v64
	v_add_f32_e32 v64, v76, v64
	v_add_f32_e32 v64, v77, v64
	v_cvt_pk_bf16_f32 v136, v72, v73
	v_cvt_pk_bf16_f32 v137, v74, v75
	ds_read_b64_tr_b16 v[148:149], v198 offset:29696
	ds_read_b64_tr_b16 v[150:151], v198 offset:30208
	v_add_f32_e32 v64, v78, v64
	v_add_f32_e32 v64, v79, v64
	v_add_f32_e32 v64, v48, v64
	v_add_f32_e32 v64, v49, v64
	v_cvt_pk_bf16_f32 v138, v76, v77
	v_cvt_pk_bf16_f32 v139, v78, v79
	v_mfma_f32_32x32x16_bf16 v[96:111], v[144:147], v[120:123], v[96:111]
	ds_read_b64_tr_b16 v[144:145], v198 offset:26624
	ds_read_b64_tr_b16 v[146:147], v198 offset:27136
	v_mfma_f32_32x32x16_bf16 v[80:95], v[176:179], v[116:119], v[80:95]
	v_add_f32_e32 v64, v50, v64
	v_add_f32_e32 v64, v51, v64
	v_add_f32_e32 v64, v52, v64
	v_add_f32_e32 v64, v53, v64
	v_cvt_pk_bf16_f32 v132, v48, v49
	v_cvt_pk_bf16_f32 v133, v50, v51
	ds_read_b64_tr_b16 v[184:185], v198 offset:30720
	ds_read_b64_tr_b16 v[186:187], v198 offset:31232
	v_add_f32_e32 v48, v54, v64
	v_add_f32_e32 v48, v55, v48
	v_add_f32_e32 v48, v56, v48
	v_add_f32_e32 v48, v57, v48
	v_cvt_pk_bf16_f32 v134, v52, v53
	v_cvt_pk_bf16_f32 v135, v54, v55
	v_mfma_f32_32x32x16_bf16 v[96:111], v[168:171], v[116:119], v[96:111]
	ds_read_b64_tr_b16 v[180:181], v198 offset:27648
	ds_read_b64_tr_b16 v[182:183], v198 offset:28160
	v_mfma_f32_32x32x16_bf16 v[80:95], v[172:175], v[112:115], v[80:95]
	v_add_f32_e32 v48, v58, v48
	v_add_f32_e32 v48, v59, v48
	v_add_f32_e32 v48, v60, v48
	v_add_f32_e32 v48, v61, v48
	v_cvt_pk_bf16_f32 v124, v56, v57
	v_cvt_pk_bf16_f32 v125, v58, v59
	ds_read_b64_tr_b16 v[176:177], v198 offset:31744
	ds_read_b64_tr_b16 v[178:179], v198 offset:32256
	v_add_f32_e32 v48, v62, v48
	v_add_f32_e32 v48, v63, v48
	v_add_f32_e32 v168, 0, v48
	v_cvt_pk_bf16_f32 v126, v60, v61
	v_cvt_pk_bf16_f32 v127, v62, v63
	v_mfma_f32_32x32x16_bf16 v[96:111], v[164:167], v[112:115], v[96:111]
	s_waitcnt lgkmcnt(8)
	ds_read_b128 v[64:67], v196 offset:256
	ds_read_b128 v[68:71], v196 offset:288
	ds_read_b128 v[72:75], v196 offset:320
	ds_read_b128 v[76:79], v196 offset:352
	ds_read_b128 v[48:51], v196 offset:384
	ds_read_b128 v[52:55], v196 offset:416
	ds_read_b128 v[56:59], v196 offset:448
	ds_read_b128 v[60:63], v196 offset:480
	s_add_i32 s0, s1, s65
	s_mov_b32 m0, s0
	s_nop 0
	global_load_lds_dwordx4 v[194:195], off
	s_add_i32 s0, s71, s68
	s_mov_b32 m0, s0
	s_nop 0
	global_load_lds_dwordx4 v[192:193], off
	s_waitcnt lgkmcnt(4)
	v_pk_add_f32 v[64:65], v[80:81], v[64:65]
	v_pk_add_f32 v[66:67], v[82:83], v[66:67]
	v_pk_add_f32 v[68:69], v[84:85], v[68:69]
	v_pk_add_f32 v[70:71], v[86:87], v[70:71]
	v_pk_add_f32 v[72:73], v[88:89], v[72:73]
	v_pk_add_f32 v[74:75], v[90:91], v[74:75]
	v_pk_add_f32 v[76:77], v[92:93], v[76:77]
	v_pk_add_f32 v[78:79], v[94:95], v[78:79]
	s_waitcnt lgkmcnt(1)
	v_pk_add_f32 v[48:49], v[96:97], v[48:49]
	v_pk_add_f32 v[50:51], v[98:99], v[50:51]
	v_pk_add_f32 v[52:53], v[100:101], v[52:53]
	v_pk_add_f32 v[54:55], v[102:103], v[54:55]
	v_pk_add_f32 v[56:57], v[104:105], v[56:57]
	v_pk_add_f32 v[58:59], v[106:107], v[58:59]
	s_waitcnt lgkmcnt(0)
	v_pk_add_f32 v[60:61], v[108:109], v[60:61]
	v_pk_add_f32 v[62:63], v[110:111], v[62:63]
	v_max_f32_e32 v80, v64, v65
	v_max3_f32 v81, v66, v67, v49
	v_max3_f32 v80, v80, v48, v50
	v_max3_f32 v80, v80, v51, v68
	v_max3_f32 v81, v81, v70, v71
	v_max3_f32 v80, v80, v69, v52
	v_max3_f32 v81, v81, v54, v55
	v_max3_f32 v80, v80, v53, v72
	v_max3_f32 v81, v81, v74, v75
	v_max3_f32 v80, v80, v73, v56
	v_max3_f32 v81, v81, v58, v59
	v_max3_f32 v80, v80, v57, v76
	v_max3_f32 v81, v81, v78, v79
	v_max3_f32 v80, v80, v77, v60
	v_max3_f32 v81, v81, v62, v63
	v_max3_f32 v80, v80, v61, v81
	v_mov_b32_e32 v81, v80
	s_nop 1
	v_permlane32_swap_b32_e32 v80, v81
	v_max_f32_e32 v81, v81, v81
	v_max_f32_e32 v80, v80, v80
	v_max_f32_e32 v80, v80, v81
	v_cmp_lt_f32_e32 vcc, s61, v80
	s_cmp_lg_u64 vcc, 0
	v_add_f32_e32 v231, v197, v168
	s_cselect_b64 s[10:11], -1, 0
	s_cbranch_vccnz .LBB0_798

; template <int MODE> __device__ __forceinline__ int pop_tile(unsigned& tiles) { int j; if (MODE == 2) { j = 31 - __builtin_clz(tiles); tiles &= ~(1u << j); } else { j = __builtin_ctz(tiles); tiles &= tiles - 1u; } return j; }
; __device__ __forceinline__ void nsa_unit(int b, int g, int tq, const Args& a, LAS unsigned char* lds, int tid, int wave, int lane, int& nxt) {
;     ...
;                 int j2, m2; if (wt) { j2 = pop_tile<2>(wt); m2 = 2; } else if (ut) { j2 = pop_tile<1>(ut); m2 = 1; } else { j2 = -1; m2 = 2; }
;                 NL_DMA(m2, (j2 >= 0 ? j2 : j0), o2);
;                 NL_STEP(2, 0u);
.LBB0_953:
	s_cmp_gt_i32 s97, -1
	s_cselect_b64 s[60:61], -1, 0
	s_cmp_lt_i32 s97, 0
	s_cselect_b32 s6, s14, s97
	s_ashr_i32 s7, s6, 31
	s_lshl_b64 s[6:7], s[6:7], 14
	s_add_u32 s4, s6, s4
	s_addc_u32 s5, s7, s5
	v_lshl_add_u64 v[2:3], v[160:161], 0, s[4:5]
	s_add_i32 s6, s51, s94
	s_mov_b32 m0, s6
	s_nop 0
	global_load_lds_dwordx4 v[2:3], off
	v_lshl_add_u64 v[2:3], v[162:163], 0, s[4:5]
	s_add_i32 s4, s51, s95
	s_add_i32 s8, s14, 3
	s_cmp_gt_i32 s8, s38
	s_mov_b32 m0, s4
	s_nop 0
	global_load_lds_dwordx4 v[2:3], off
	s_cselect_b64 s[6:7], -1, 0
	s_add_i32 s4, s14, 8
	s_cmp_eq_u32 s4, s38
	s_cselect_b64 s[4:5], -1, 0
	s_or_b64 s[10:11], s[6:7], s[4:5]
	s_mov_b64 s[6:7], -1
	s_and_b64 vcc, exec, s[10:11]
	s_cbranch_vccnz .LBB0_955
	s_add_i32 s6, s50, 0
	v_add_u32_e32 v6, s6, v183
	ds_read_b128 v[2:5], v6
	ds_read_b128 v[6:9], v6 offset:4096
	v_sub_f32_e32 v80, v185, v0
	v_mov_b32_e32 v81, v80
	v_mov_b32_e32 v82, v80
	v_mov_b32_e32 v83, v80
	v_mov_b32_e32 v84, v80
	v_mov_b32_e32 v85, v80
	v_mov_b32_e32 v86, v80
	v_mov_b32_e32 v87, v80
	v_mov_b32_e32 v88, v80
	v_mov_b32_e32 v89, v80
	v_mov_b32_e32 v90, v80
	v_mov_b32_e32 v91, v80
	v_mov_b32_e32 v92, v80
	v_mov_b32_e32 v93, v80
	v_mov_b32_e32 v94, v80
	v_mov_b32_e32 v95, v80
	v_add_u32_e32 v194, s6, v184
	v_add_u32_e32 v195, s6, v186
	v_add_u32_e32 v212, s6, v187
	ds_read_b128 v[196:199], v194
	ds_read_b128 v[200:203], v194 offset:4096
	ds_read_b128 v[204:207], v195
	ds_read_b128 v[208:211], v195 offset:4096
	ds_read_b128 v[216:219], v212
	ds_read_b128 v[220:223], v212 offset:4096
	s_mov_b64 s[6:7], 0
	s_waitcnt lgkmcnt(6)
	s_nop 0
	v_mfma_f32_32x32x16_bf16 v[96:111], v[2:5], v[144:147], v[80:95]
	v_mfma_f32_32x32x16_bf16 v[80:95], v[6:9], v[144:147], v[80:95]
	s_waitcnt lgkmcnt(4)
	v_mfma_f32_32x32x16_bf16 v[96:111], v[196:199], v[148:151], v[96:111]
	v_mfma_f32_32x32x16_bf16 v[80:95], v[200:203], v[148:151], v[80:95]
	s_waitcnt lgkmcnt(2)
	v_mfma_f32_32x32x16_bf16 v[96:111], v[204:207], v[152:155], v[96:111]
	v_mfma_f32_32x32x16_bf16 v[80:95], v[208:211], v[152:155], v[80:95]
	s_waitcnt lgkmcnt(0)
	v_mfma_f32_32x32x16_bf16 v[96:111], v[216:219], v[156:159], v[96:111]
	v_mfma_f32_32x32x16_bf16 v[80:95], v[220:223], v[156:159], v[80:95]

.LBB0_964:
	s_add_i32 s4, s50, 0
	v_add_u32_e32 v6, s4, v183
	ds_read_b128 v[2:5], v6
	ds_read_b128 v[6:9], v6 offset:4096
	v_add_u32_e32 v194, s4, v184
	v_add_u32_e32 v195, s4, v186
	v_add_u32_e32 v212, s4, v187
	ds_read_b128 v[196:199], v194
	ds_read_b128 v[200:203], v194 offset:4096
	ds_read_b128 v[204:207], v195
	ds_read_b128 v[208:211], v195 offset:4096
	ds_read_b128 v[216:219], v212
	ds_read_b128 v[220:223], v212 offset:4096
	s_waitcnt lgkmcnt(6)
	v_mfma_f32_32x32x16_bf16 v[96:111], v[2:5], v[144:147], v[96:111]
	v_mfma_f32_32x32x16_bf16 v[80:95], v[6:9], v[144:147], v[80:95]
	s_waitcnt lgkmcnt(4)
	v_mfma_f32_32x32x16_bf16 v[96:111], v[196:199], v[148:151], v[96:111]
	v_mfma_f32_32x32x16_bf16 v[80:95], v[200:203], v[148:151], v[80:95]
	s_waitcnt lgkmcnt(2)
	v_mfma_f32_32x32x16_bf16 v[96:111], v[204:207], v[152:155], v[96:111]
	v_mfma_f32_32x32x16_bf16 v[80:95], v[208:211], v[152:155], v[80:95]
	s_waitcnt lgkmcnt(0)
	v_mfma_f32_32x32x16_bf16 v[96:111], v[216:219], v[156:159], v[96:111]
	v_mfma_f32_32x32x16_bf16 v[80:95], v[220:223], v[156:159], v[80:95]

; template <int MODE> __device__ __forceinline__ int pop_tile(unsigned& tiles) { int j; if (MODE == 2) { j = 31 - __builtin_clz(tiles); tiles &= ~(1u << j); } else { j = __builtin_ctz(tiles); tiles &= tiles - 1u; } return j; }
; __device__ __forceinline__ void nsa_unit(int b, int g, int tq, const Args& a, LAS unsigned char* lds, int tid, int wave, int lane, int& nxt) {
;     ...
;             for (;;) {
;                 const int j2 = ut ? pop_tile<1>(ut) : -1;
;                 NL_DMA(1, (j2 >= 0 ? j2 : j0), o2);
;                 NL_STEP(1, selbits);
.LBB0_975:
	s_sub_i32 s10, 28, s67
	v_sub_co_u32_e64 v0, s[6:7], s0, 1
	s_ff1_i32_b32 s11, s0
	s_and_b64 s[4:5], s[6:7], exec
	s_cselect_b32 s4, s44, s11
	s_ashr_i32 s5, s4, 31
	s_lshl_b64 s[4:5], s[4:5], 14
	v_lshl_add_u64 v[2:3], v[160:161], 0, s[4:5]
	s_add_i32 s8, s50, s94
	s_mov_b32 m0, s8
	s_nop 0
	global_load_lds_dwordx4 v[2:3], off
	v_lshl_add_u64 v[2:3], v[162:163], 0, s[4:5]
	s_add_i32 s4, s50, s95
	s_mov_b32 m0, s4
	s_nop 0
	global_load_lds_dwordx4 v[2:3], off
	v_readfirstlane_b32 s12, v0
	v_bfe_u32 v0, v164, s44, 1
	s_cmp_gt_i32 s44, s10
	v_cmp_eq_u32_e64 s[4:5], 0, v0
	s_mov_b64 s[8:9], -1
	s_cbranch_scc1 .LBB0_977
	s_add_i32 s8, s1, 0
	v_add_u32_e32 v0, s8, v183
	ds_read_b128 v[2:5], v0
	ds_read_b128 v[6:9], v0 offset:4096
	v_cndmask_b32_e64 v80, v185, v173, s[4:5]
	v_mov_b32_e32 v81, v80
	v_mov_b32_e32 v82, v80
	v_mov_b32_e32 v83, v80
	v_mov_b32_e32 v84, v80
	v_mov_b32_e32 v85, v80
	v_mov_b32_e32 v86, v80
	v_mov_b32_e32 v87, v80
	v_mov_b32_e32 v88, v80
	v_mov_b32_e32 v89, v80
	v_mov_b32_e32 v90, v80
	v_mov_b32_e32 v91, v80
	v_mov_b32_e32 v92, v80
	v_mov_b32_e32 v93, v80
	v_mov_b32_e32 v94, v80
	v_mov_b32_e32 v95, v80
	v_add_u32_e32 v0, s8, v184
	v_add_u32_e32 v194, s8, v184
	v_add_u32_e32 v195, s8, v186
	v_add_u32_e32 v212, s8, v187
	ds_read_b128 v[196:199], v194
	ds_read_b128 v[200:203], v194 offset:4096
	ds_read_b128 v[204:207], v195
	ds_read_b128 v[208:211], v195 offset:4096
	ds_read_b128 v[216:219], v212
	ds_read_b128 v[220:223], v212 offset:4096
	s_mov_b64 s[8:9], 0
	s_waitcnt lgkmcnt(6)
	v_mfma_f32_32x32x16_bf16 v[96:111], v[2:5], v[144:147], v[80:95]
	v_mfma_f32_32x32x16_bf16 v[80:95], v[6:9], v[144:147], v[80:95]
	s_waitcnt lgkmcnt(4)
	v_mfma_f32_32x32x16_bf16 v[96:111], v[196:199], v[148:151], v[96:111]
	v_mfma_f32_32x32x16_bf16 v[80:95], v[200:203], v[148:151], v[80:95]
	s_waitcnt lgkmcnt(2)
	v_mfma_f32_32x32x16_bf16 v[96:111], v[204:207], v[152:155], v[96:111]
	v_mfma_f32_32x32x16_bf16 v[80:95], v[208:211], v[152:155], v[80:95]
	s_waitcnt lgkmcnt(0)
	v_mfma_f32_32x32x16_bf16 v[96:111], v[216:219], v[156:159], v[96:111]
	v_mfma_f32_32x32x16_bf16 v[80:95], v[220:223], v[156:159], v[80:95]
.LBB0_977:
	s_andn2_b64 vcc, exec, s[8:9]
	s_cbranch_vccnz .LBB0_979
	v_lshl_or_b32 v0, s44, 6, v179
	v_sub_u32_e32 v0, v178, v0
	v_lshl_add_u32 v0, v0, 2, s96
	ds_read2_b32 v[6:7], v0 offset0:63 offset1:64
	ds_read2_b32 v[8:9], v0 offset0:61 offset1:62
	ds_read2_b32 v[10:11], v0 offset0:55 offset1:56
	ds_read2_b32 v[12:13], v0 offset0:53 offset1:54
	ds_read2_b32 v[14:15], v0 offset0:31 offset1:32
	s_nop 1
	ds_read2_b32 v[80:81], v0 offset0:29 offset1:30
	ds_read2_b32 v[82:83], v0 offset0:23 offset1:24
	ds_read2_b32 v[84:85], v0 offset0:21 offset1:22
	ds_read2_b32 v[2:3], v0 offset0:15 offset1:16
	ds_read2_b32 v[4:5], v0 offset0:13 offset1:14
	ds_read2_b32 v[86:87], v0 offset0:7 offset1:8
	ds_read2_b32 v[88:89], v0 offset0:5 offset1:6
	ds_read2_b32 v[96:97], v0 offset0:47 offset1:48
	ds_read2_b32 v[98:99], v0 offset0:45 offset1:46
	ds_read2_b32 v[100:101], v0 offset0:39 offset1:40
	ds_read2_b32 v[102:103], v0 offset0:37 offset1:38
	s_add_i32 s8, s1, 0
	v_add_u32_e32 v0, s8, v183
	s_waitcnt lgkmcnt(4)
	v_cndmask_b32_e64 v95, v88, v173, s[4:5]
	v_cndmask_b32_e64 v94, v89, v173, s[4:5]
	v_cndmask_b32_e64 v91, v4, v173, s[4:5]
	v_cndmask_b32_e64 v90, v5, v173, s[4:5]
	v_cndmask_b32_e64 v89, v2, v173, s[4:5]
	v_cndmask_b32_e64 v88, v3, v173, s[4:5]
	s_waitcnt lgkmcnt(2)
	v_cndmask_b32_e64 v107, v98, v173, s[4:5]
	v_cndmask_b32_e64 v106, v99, v173, s[4:5]
	v_cndmask_b32_e64 v105, v96, v173, s[4:5]
	v_cndmask_b32_e64 v104, v97, v173, s[4:5]
	ds_read_b128 v[2:5], v0
	v_cndmask_b32_e64 v99, v8, v173, s[4:5]
	v_cndmask_b32_e64 v98, v9, v173, s[4:5]
	v_cndmask_b32_e64 v97, v6, v173, s[4:5]
	v_cndmask_b32_e64 v96, v7, v173, s[4:5]
	ds_read_b128 v[6:9], v0 offset:4096
	v_cndmask_b32_e64 v93, v86, v173, s[4:5]
	v_cndmask_b32_e64 v92, v87, v173, s[4:5]
	v_cndmask_b32_e64 v87, v84, v173, s[4:5]
	s_waitcnt lgkmcnt(2)
	v_cndmask_b32_e64 v111, v102, v173, s[4:5]
	v_cndmask_b32_e64 v110, v103, v173, s[4:5]
	v_cndmask_b32_e64 v109, v100, v173, s[4:5]
	v_cndmask_b32_e64 v108, v101, v173, s[4:5]
	v_cndmask_b32_e64 v103, v12, v173, s[4:5]
	v_cndmask_b32_e64 v102, v13, v173, s[4:5]
	v_cndmask_b32_e64 v101, v10, v173, s[4:5]
	v_cndmask_b32_e64 v100, v11, v173, s[4:5]
	v_cndmask_b32_e64 v86, v85, v173, s[4:5]
	v_cndmask_b32_e64 v85, v82, v173, s[4:5]
	v_cndmask_b32_e64 v84, v83, v173, s[4:5]
	v_cndmask_b32_e64 v83, v80, v173, s[4:5]
	v_cndmask_b32_e64 v82, v81, v173, s[4:5]
	v_cndmask_b32_e64 v81, v14, v173, s[4:5]
	v_cndmask_b32_e64 v80, v15, v173, s[4:5]
	v_add_u32_e32 v194, s8, v184
	v_add_u32_e32 v195, s8, v186
	v_add_u32_e32 v212, s8, v187
	ds_read_b128 v[196:199], v194
	ds_read_b128 v[200:203], v194 offset:4096
	ds_read_b128 v[204:207], v195
	ds_read_b128 v[208:211], v195 offset:4096
	ds_read_b128 v[216:219], v212
	ds_read_b128 v[220:223], v212 offset:4096
	s_waitcnt lgkmcnt(6)
	v_mfma_f32_32x32x16_bf16 v[96:111], v[2:5], v[144:147], v[96:111]
	v_mfma_f32_32x32x16_bf16 v[80:95], v[6:9], v[144:147], v[80:95]
	s_waitcnt lgkmcnt(4)
	v_mfma_f32_32x32x16_bf16 v[96:111], v[196:199], v[148:151], v[96:111]
	v_mfma_f32_32x32x16_bf16 v[80:95], v[200:203], v[148:151], v[80:95]
	s_waitcnt lgkmcnt(2)
	v_mfma_f32_32x32x16_bf16 v[96:111], v[204:207], v[152:155], v[96:111]
	v_mfma_f32_32x32x16_bf16 v[80:95], v[208:211], v[152:155], v[80:95]
	s_waitcnt lgkmcnt(0)
	v_mfma_f32_32x32x16_bf16 v[96:111], v[216:219], v[156:159], v[96:111]
	v_mfma_f32_32x32x16_bf16 v[80:95], v[220:223], v[156:159], v[80:95]

; template <int MODE> __device__ __forceinline__ int pop_tile(unsigned& tiles) { int j; if (MODE == 2) { j = 31 - __builtin_clz(tiles); tiles &= ~(1u << j); } else { j = __builtin_ctz(tiles); tiles &= tiles - 1u; } return j; }
; __device__ __forceinline__ void nsa_unit(int b, int g, int tq, const Args& a, LAS unsigned char* lds, int tid, int wave, int lane, int& nxt) {
;     ...
;             for (;;) {
;                 const int j2 = ut ? pop_tile<1>(ut) : -1;
;                 NL_DMA(1, (j2 >= 0 ? j2 : j0), o2);
;                 NL_STEP(1, selbits);
.LBB0_981:
	v_sub_co_u32_e64 v2, s[6:7], s0, 1
	s_mov_b32 s11, s4
	s_mov_b32 s12, s50
	s_mov_b32 s50, s1
	s_ff1_i32_b32 s1, s0
	s_and_b64 s[4:5], s[6:7], exec
	s_cselect_b32 s44, s97, s1
	s_lshl_b64 s[4:5], s[44:45], 14
	v_readfirstlane_b32 s13, v2
	v_lshl_add_u64 v[2:3], v[160:161], 0, s[4:5]
	s_add_i32 s8, s50, s94
	s_mov_b32 m0, s8
	s_nop 0
	global_load_lds_dwordx4 v[2:3], off
	v_lshl_add_u64 v[2:3], v[162:163], 0, s[4:5]
	s_add_i32 s4, s50, s95
	s_mov_b32 m0, s4
	s_nop 0
	global_load_lds_dwordx4 v[2:3], off
	v_bfe_u32 v2, v164, s97, 1
	s_cmp_gt_i32 s97, s10
	v_cmp_eq_u32_e64 s[4:5], 0, v2
	s_mov_b64 s[8:9], -1
	s_cbranch_scc1 .LBB0_983
	s_add_i32 s8, s51, 0
	v_sub_f32_e32 v2, v185, v0
	v_add_u32_e32 v6, s8, v183
	v_cndmask_b32_e64 v112, v2, v173, s[4:5]
	ds_read_b128 v[2:5], v6
	ds_read_b128 v[6:9], v6 offset:4096
	v_mov_b32_e32 v113, v112
	v_mov_b32_e32 v114, v112
	v_mov_b32_e32 v115, v112
	v_mov_b32_e32 v116, v112
	v_mov_b32_e32 v117, v112
	v_mov_b32_e32 v118, v112
	v_mov_b32_e32 v119, v112
	v_mov_b32_e32 v120, v112
	v_mov_b32_e32 v121, v112
	v_mov_b32_e32 v122, v112
	v_mov_b32_e32 v123, v112
	v_mov_b32_e32 v124, v112
	v_mov_b32_e32 v125, v112
	v_mov_b32_e32 v126, v112
	v_mov_b32_e32 v127, v112
	v_add_u32_e32 v194, s8, v184
	v_add_u32_e32 v195, s8, v186
	v_add_u32_e32 v212, s8, v187
	ds_read_b128 v[196:199], v194
	ds_read_b128 v[200:203], v194 offset:4096
	ds_read_b128 v[204:207], v195
	ds_read_b128 v[208:211], v195 offset:4096
	ds_read_b128 v[216:219], v212
	ds_read_b128 v[220:223], v212 offset:4096
	s_mov_b64 s[8:9], 0
	s_waitcnt lgkmcnt(6)
	s_nop 0
	v_mfma_f32_32x32x16_bf16 v[128:143], v[2:5], v[144:147], v[112:127]
	v_mfma_f32_32x32x16_bf16 v[112:127], v[6:9], v[144:147], v[112:127]
	s_waitcnt lgkmcnt(4)
	v_mfma_f32_32x32x16_bf16 v[128:143], v[196:199], v[148:151], v[128:143]
	v_mfma_f32_32x32x16_bf16 v[112:127], v[200:203], v[148:151], v[112:127]
	s_waitcnt lgkmcnt(2)
	v_mfma_f32_32x32x16_bf16 v[128:143], v[204:207], v[152:155], v[128:143]
	v_mfma_f32_32x32x16_bf16 v[112:127], v[208:211], v[152:155], v[112:127]
	s_waitcnt lgkmcnt(0)
	v_mfma_f32_32x32x16_bf16 v[128:143], v[216:219], v[156:159], v[128:143]
	v_mfma_f32_32x32x16_bf16 v[112:127], v[220:223], v[156:159], v[112:127]
; #define LAS __attribute__((address_space(3)))
;     ...
;         } else { LAS const float* ab = aux + (t - kb + 1);
; #pragma unroll
;             for (int r = 0; r < 16; ++r) { X0[r] = ab[63 - ((r & 3) + 8 * (r >> 2))] - m; X1[r] = ab[31 - ((r & 3) + 8 * (r >> 2))] - m; }
;             if (MODE == 1 && !sel) {
; #pragma unroll
;                 for (int r = 0; r < 16; ++r) { X0[r] = NEG; X1[r] = NEG; } }
.LBB0_983:
	s_andn2_b64 vcc, exec, s[8:9]
	s_cbranch_vccnz .LBB0_985
	v_lshl_or_b32 v2, s97, 6, v179
	v_sub_u32_e32 v2, v178, v2
	s_nop 7
	v_lshl_add_u32 v126, v2, 2, s96
	ds_read2_b32 v[2:3], v126 offset0:63 offset1:64
	ds_read2_b32 v[4:5], v126 offset0:31 offset1:32
	ds_read2_b32 v[6:7], v126 offset0:61 offset1:62
	ds_read2_b32 v[8:9], v126 offset0:29 offset1:30
	s_add_i32 s8, s51, 0
	s_waitcnt lgkmcnt(3)
	v_pk_add_f32 v[10:11], v[2:3], v[0:1] op_sel_hi:[1,0] neg_lo:[0,1] neg_hi:[0,1]
	ds_read2_b32 v[2:3], v126 offset0:55 offset1:56
	s_waitcnt lgkmcnt(3)
	v_pk_add_f32 v[12:13], v[4:5], v[0:1] op_sel_hi:[1,0] neg_lo:[0,1] neg_hi:[0,1]
	ds_read2_b32 v[4:5], v126 offset0:23 offset1:24
	ds_read2_b32 v[116:117], v126 offset0:15 offset1:16
	ds_read2_b32 v[118:119], v126 offset0:13 offset1:14
	s_waitcnt lgkmcnt(3)
	v_pk_add_f32 v[112:113], v[2:3], v[0:1] op_sel_hi:[1,0] neg_lo:[0,1] neg_hi:[0,1]
	ds_read2_b32 v[2:3], v126 offset0:21 offset1:22
	v_pk_add_f32 v[14:15], v[8:9], v[0:1] op_sel_hi:[1,0] neg_lo:[0,1] neg_hi:[0,1]
	ds_read2_b32 v[8:9], v126 offset0:53 offset1:54
	ds_read2_b32 v[120:121], v126 offset0:39 offset1:40
	s_waitcnt lgkmcnt(5)
	v_pk_add_f32 v[114:115], v[4:5], v[0:1] op_sel_hi:[1,0] neg_lo:[0,1] neg_hi:[0,1]
	ds_read2_b32 v[4:5], v126 offset0:47 offset1:48
	s_waitcnt lgkmcnt(3)
	v_pk_add_f32 v[190:191], v[2:3], v[0:1] op_sel_hi:[1,0] neg_lo:[0,1] neg_hi:[0,1]
	ds_read2_b32 v[2:3], v126 offset0:45 offset1:46
	ds_read2_b32 v[122:123], v126 offset0:7 offset1:8
	ds_read2_b32 v[124:125], v126 offset0:37 offset1:38
	ds_read2_b32 v[126:127], v126 offset0:5 offset1:6
	s_waitcnt lgkmcnt(6)
	v_pk_add_f32 v[8:9], v[8:9], v[0:1] op_sel_hi:[1,0] neg_lo:[0,1] neg_hi:[0,1]
	v_pk_add_f32 v[6:7], v[6:7], v[0:1] op_sel_hi:[1,0] neg_lo:[0,1] neg_hi:[0,1]
	s_waitcnt lgkmcnt(4)
	v_pk_add_f32 v[4:5], v[4:5], v[0:1] op_sel_hi:[1,0] neg_lo:[0,1] neg_hi:[0,1]
	s_waitcnt lgkmcnt(3)
	v_pk_add_f32 v[2:3], v[2:3], v[0:1] op_sel_hi:[1,0] neg_lo:[0,1] neg_hi:[0,1]
	s_waitcnt lgkmcnt(1)
	v_pk_add_f32 v[130:131], v[124:125], v[0:1] op_sel_hi:[1,0] neg_lo:[0,1] neg_hi:[0,1]
	v_cndmask_b32_e64 v135, v8, v173, s[4:5]
	v_add_u32_e32 v8, s8, v183
	v_cndmask_b32_e64 v143, v130, v173, s[4:5]
	v_cndmask_b32_e64 v142, v131, v173, s[4:5]
	v_cndmask_b32_e64 v139, v2, v173, s[4:5]
	v_cndmask_b32_e64 v138, v3, v173, s[4:5]
	v_cndmask_b32_e64 v137, v4, v173, s[4:5]
	v_cndmask_b32_e64 v136, v5, v173, s[4:5]
	ds_read_b128 v[2:5], v8
	v_cndmask_b32_e64 v134, v9, v173, s[4:5]
	v_cndmask_b32_e64 v131, v6, v173, s[4:5]
	v_cndmask_b32_e64 v130, v7, v173, s[4:5]
	ds_read_b128 v[6:9], v8 offset:4096
	v_pk_add_f32 v[116:117], v[116:117], v[0:1] op_sel_hi:[1,0] neg_lo:[0,1] neg_hi:[0,1]
	v_pk_add_f32 v[118:119], v[118:119], v[0:1] op_sel_hi:[1,0] neg_lo:[0,1] neg_hi:[0,1]
	v_pk_add_f32 v[128:129], v[120:121], v[0:1] op_sel_hi:[1,0] neg_lo:[0,1] neg_hi:[0,1]
	v_pk_add_f32 v[120:121], v[122:123], v[0:1] op_sel_hi:[1,0] neg_lo:[0,1] neg_hi:[0,1]
	s_waitcnt lgkmcnt(2)
	v_pk_add_f32 v[122:123], v[126:127], v[0:1] op_sel_hi:[1,0] neg_lo:[0,1] neg_hi:[0,1]
	v_cndmask_b32_e64 v125, v120, v173, s[4:5]
	v_cndmask_b32_e64 v127, v122, v173, s[4:5]
	v_cndmask_b32_e64 v126, v123, v173, s[4:5]
	v_cndmask_b32_e64 v124, v121, v173, s[4:5]
	v_cndmask_b32_e64 v123, v118, v173, s[4:5]
	v_cndmask_b32_e64 v122, v119, v173, s[4:5]
	v_cndmask_b32_e64 v121, v116, v173, s[4:5]
	v_cndmask_b32_e64 v120, v117, v173, s[4:5]
	v_cndmask_b32_e64 v119, v190, v173, s[4:5]
	v_cndmask_b32_e64 v141, v128, v173, s[4:5]
	v_cndmask_b32_e64 v140, v129, v173, s[4:5]
	v_cndmask_b32_e64 v133, v112, v173, s[4:5]
	v_cndmask_b32_e64 v132, v113, v173, s[4:5]
	v_cndmask_b32_e64 v129, v10, v173, s[4:5]
	v_cndmask_b32_e64 v128, v11, v173, s[4:5]
	v_cndmask_b32_e64 v118, v191, v173, s[4:5]
	v_cndmask_b32_e64 v117, v114, v173, s[4:5]
	v_cndmask_b32_e64 v116, v115, v173, s[4:5]
	v_cndmask_b32_e64 v115, v14, v173, s[4:5]
	v_cndmask_b32_e64 v114, v15, v173, s[4:5]
	v_cndmask_b32_e64 v113, v12, v173, s[4:5]
	v_cndmask_b32_e64 v112, v13, v173, s[4:5]
	v_add_u32_e32 v194, s8, v184
	v_add_u32_e32 v195, s8, v186
	v_add_u32_e32 v212, s8, v187
	ds_read_b128 v[196:199], v194
	ds_read_b128 v[200:203], v194 offset:4096
	ds_read_b128 v[204:207], v195
	ds_read_b128 v[208:211], v195 offset:4096
	ds_read_b128 v[216:219], v212
	ds_read_b128 v[220:223], v212 offset:4096
	s_waitcnt lgkmcnt(6)
	v_mfma_f32_32x32x16_bf16 v[128:143], v[2:5], v[144:147], v[128:143]
	v_mfma_f32_32x32x16_bf16 v[112:127], v[6:9], v[144:147], v[112:127]
	s_waitcnt lgkmcnt(4)
	v_mfma_f32_32x32x16_bf16 v[128:143], v[196:199], v[148:151], v[128:143]
	v_mfma_f32_32x32x16_bf16 v[112:127], v[200:203], v[148:151], v[112:127]
	s_waitcnt lgkmcnt(2)
	v_mfma_f32_32x32x16_bf16 v[128:143], v[204:207], v[152:155], v[128:143]
	v_mfma_f32_32x32x16_bf16 v[112:127], v[208:211], v[152:155], v[112:127]
	s_waitcnt lgkmcnt(0)
	v_mfma_f32_32x32x16_bf16 v[128:143], v[216:219], v[156:159], v[128:143]
	v_mfma_f32_32x32x16_bf16 v[112:127], v[220:223], v[156:159], v[112:127]
